# v61 + layer-1 W_in transposes moved from the prologue to the end of layer 0's mixer phase, static split over all workgroups (no atomics)
# speedup vs baseline: 1.0156x; 1.0045x over previous
; #define GAS __attribute__((address_space(1)))
; __device__ __forceinline__ unsigned cvt_pk_bf16(float lo, float hi) { const f32x2 v = {lo, hi}; return __builtin_bit_cast(unsigned, __builtin_convertvector(v, bf16n2)); }
;     __device__ __forceinline__ int lane_() const { return lane_id(); }
; #define F_w_in F.in(8)
; __device__ __forceinline__ void p0_transpose_item(const GAS float* W, int K, int N, GAS bf16* WT, int item, int lane) {
;     const int nblk = N / 64, kb = item / nblk, nb = item - kb * nblk, r = lane >> 4, c4 = lane & 15;
;     const GAS float* src = W + (size_t)(64 * kb + 16 * r) * N + 64 * nb + 4 * c4;
;     f32x4 v[16];
; #pragma unroll
;     for (int i = 0; i < 16; ++i) v[i] = __builtin_nontemporal_load((const GAS f32x4*)(src + (size_t)i * N));
;     GAS bf16* dst = WT + (size_t)(64 * nb + 4 * c4) * K + 64 * kb + 16 * r;
; #pragma unroll
;     for (int j = 0; j < 4; ++j) { v4u a, b;
;         a.x = cvt_pk_bf16(v[0][j], v[1][j]); a.y = cvt_pk_bf16(v[2][j], v[3][j]); a.z = cvt_pk_bf16(v[4][j], v[5][j]); a.w = cvt_pk_bf16(v[6][j], v[7][j]);
;         b.x = cvt_pk_bf16(v[8][j], v[9][j]); b.y = cvt_pk_bf16(v[10][j], v[11][j]); b.z = cvt_pk_bf16(v[12][j], v[13][j]); b.w = cvt_pk_bf16(v[14][j], v[15][j]);
;         *(GAS v4u*)(dst + (size_t)j * K) = a; *(GAS v4u*)(dst + (size_t)j * K + 8) = b; }
; }
; __device__ __forceinline__ void phase_prologue(Frame& F) {
;     ...
;     for (int it = gw; it < NITEMS; it += NGW) {
;         int r = it;
;         if (r < 2 * I_IN) { const int l = r / I_IN; p0_transpose_item(F_w_in + (size_t)l * D * NPROJ, D, NPROJ, win_t + (size_t)l * NPROJ * D, r % I_IN, F.lane_()); continue; } r -= 2 * I_IN;
;         if (r < 6 * I_SQ) { const int m = r / I_SQ; p0_transpose_item(F_w_branch + (size_t)m * D * D, D, D, wbr_t + (size_t)m * D * D, r % I_SQ, F.lane_()); continue; } r -= 6 * I_SQ;
;         if (r < 2 * I_SQ) { const int m = r / I_SQ; p0_transpose_item(F_w_out + (size_t)m * D * D, D, D, wout_t + (size_t)m * D * D, r % I_SQ, F.lane_()); continue; } r -= 2 * I_SQ;
;         { const int m = r / I_PL; p0_transpose_item(F_w_pool + (size_t)m * 65536, 256, 256, wpool_t + (size_t)m * 65536, r % I_PL, F.lane_()); }
;     }
.LBB0_881:
	v_readlane_b32 s8, v240, 7
	s_cmp_lg_u32 s8, 0
	s_cbranch_scc1 .Ldu_done
	v_mbcnt_lo_u32_b32 v182, -1, 0
	v_mbcnt_hi_u32_b32 v182, -1, v182
	v_mov_b32_e32 v188, 0x27d40
	v_mov_b32_e32 v190, s18
	ds_read_b64 v[188:189], v188
	ds_read_b64 v[190:191], v190
	v_lshrrev_b32_e32 v183, 4, v182
	v_and_b32_e32 v184, 15, v182
	v_mul_u32_u24_e32 v185, 0xd0000, v183
	v_lshl_add_u32 v185, v184, 4, v185
	v_lshlrev_b32_e32 v186, 13, v184
	v_lshl_add_u32 v186, v183, 5, v186
	v_add_u32_e32 v187, 0x1000, v186
	s_waitcnt lgkmcnt(0)
	v_readfirstlane_b32 s16, v188
	v_readfirstlane_b32 s17, v189
	v_readfirstlane_b32 s14, v190
	v_readfirstlane_b32 s15, v191
	s_add_u32 s16, s16, 0x3400000
	s_addc_u32 s17, s17, 0
	s_add_u32 s64, s14, 0x1c00000
	s_addc_u32 s65, s15, 0
	s_lshl_b32 s61, s101, 3
	s_lshr_b32 s8, s95, 10
	s_add_u32 s61, s61, s8
	s_branch .Ldu_first
.Ldu_next:
	s_addk_i32 s61, 0x800
.Ldu_first:
	s_cmpk_gt_u32 s61, 0xcff
	s_cbranch_scc1 .Ldu_done
	s_mul_i32 s8, s61, 0x4ec5
	s_lshr_b32 s8, s8, 22
	s_mul_i32 s9, s8, 0xd0
	s_sub_u32 s9, s61, s9
	s_mul_i32 s20, s8, 0x340000
	s_lshl_b32 s32, s9, 8
	s_add_u32 s20, s20, s32
	s_add_u32 s66, s16, s20
	s_addc_u32 s67, s17, 0
	global_load_dwordx4 v[80:83], v185, s[66:67] nt
	s_add_u32 s66, s66, 0xd000
	s_addc_u32 s67, s67, 0
	global_load_dwordx4 v[84:87], v185, s[66:67] nt
	s_add_u32 s66, s66, 0xd000
	s_addc_u32 s67, s67, 0
	global_load_dwordx4 v[88:91], v185, s[66:67] nt
	s_add_u32 s66, s66, 0xd000
	s_addc_u32 s67, s67, 0
	global_load_dwordx4 v[92:95], v185, s[66:67] nt
	s_add_u32 s66, s66, 0xd000
	s_addc_u32 s67, s67, 0
	global_load_dwordx4 v[96:99], v185, s[66:67] nt
	s_add_u32 s66, s66, 0xd000
	s_addc_u32 s67, s67, 0
	global_load_dwordx4 v[100:103], v185, s[66:67] nt
	s_add_u32 s66, s66, 0xd000
	s_addc_u32 s67, s67, 0
	global_load_dwordx4 v[104:107], v185, s[66:67] nt
	s_add_u32 s66, s66, 0xd000
	s_addc_u32 s67, s67, 0
	global_load_dwordx4 v[108:111], v185, s[66:67] nt
	s_add_u32 s66, s66, 0xd000
	s_addc_u32 s67, s67, 0
	global_load_dwordx4 v[128:131], v185, s[66:67] nt
	s_add_u32 s66, s66, 0xd000
	s_addc_u32 s67, s67, 0
	global_load_dwordx4 v[132:135], v185, s[66:67] nt
	s_add_u32 s66, s66, 0xd000
	s_addc_u32 s67, s67, 0
	global_load_dwordx4 v[136:139], v185, s[66:67] nt
	s_add_u32 s66, s66, 0xd000
	s_addc_u32 s67, s67, 0
	global_load_dwordx4 v[140:143], v185, s[66:67] nt
	s_add_u32 s66, s66, 0xd000
	s_addc_u32 s67, s67, 0
	global_load_dwordx4 v[144:147], v185, s[66:67] nt
	s_add_u32 s66, s66, 0xd000
	s_addc_u32 s67, s67, 0
	global_load_dwordx4 v[152:155], v185, s[66:67] nt
	s_add_u32 s66, s66, 0xd000
	s_addc_u32 s67, s67, 0
	global_load_dwordx4 v[156:159], v185, s[66:67] nt
	s_add_u32 s66, s66, 0xd000
	s_addc_u32 s67, s67, 0
	global_load_dwordx4 v[160:163], v185, s[66:67] nt
	s_lshl_b32 s20, s9, 17
	s_lshl_b32 s32, s8, 7
	s_add_u32 s20, s20, s32
	s_add_u32 s68, s64, s20
	s_addc_u32 s69, s65, 0
	s_waitcnt vmcnt(0)
	v_cvt_pk_bf16_f32 v164, v80, v84
	v_cvt_pk_bf16_f32 v165, v88, v92
	v_cvt_pk_bf16_f32 v166, v96, v100
	v_cvt_pk_bf16_f32 v167, v104, v108
	v_cvt_pk_bf16_f32 v168, v128, v132
	v_cvt_pk_bf16_f32 v169, v136, v140
	v_cvt_pk_bf16_f32 v170, v144, v152
	v_cvt_pk_bf16_f32 v171, v156, v160
	global_store_dwordx4 v186, v[164:167], s[68:69]
	global_store_dwordx4 v186, v[168:171], s[68:69] offset:16
	v_cvt_pk_bf16_f32 v192, v81, v85
	v_cvt_pk_bf16_f32 v193, v89, v93
	v_cvt_pk_bf16_f32 v194, v97, v101
	v_cvt_pk_bf16_f32 v195, v105, v109
	v_cvt_pk_bf16_f32 v196, v129, v133
	v_cvt_pk_bf16_f32 v197, v137, v141
	v_cvt_pk_bf16_f32 v198, v145, v153
	v_cvt_pk_bf16_f32 v199, v157, v161
	global_store_dwordx4 v186, v[192:195], s[68:69] offset:2048
	global_store_dwordx4 v186, v[196:199], s[68:69] offset:2064
	v_cvt_pk_bf16_f32 v164, v82, v86
	v_cvt_pk_bf16_f32 v165, v90, v94
	v_cvt_pk_bf16_f32 v166, v98, v102
	v_cvt_pk_bf16_f32 v167, v106, v110
	v_cvt_pk_bf16_f32 v168, v130, v134
	v_cvt_pk_bf16_f32 v169, v138, v142
	v_cvt_pk_bf16_f32 v170, v146, v154
	v_cvt_pk_bf16_f32 v171, v158, v162
	global_store_dwordx4 v187, v[164:167], s[68:69]
	global_store_dwordx4 v187, v[168:171], s[68:69] offset:16
	v_cvt_pk_bf16_f32 v192, v83, v87
	v_cvt_pk_bf16_f32 v193, v91, v95
	v_cvt_pk_bf16_f32 v194, v99, v103
	v_cvt_pk_bf16_f32 v195, v107, v111
	v_cvt_pk_bf16_f32 v196, v131, v135
	v_cvt_pk_bf16_f32 v197, v139, v143
	v_cvt_pk_bf16_f32 v198, v147, v155
	v_cvt_pk_bf16_f32 v199, v159, v163
	global_store_dwordx4 v187, v[192:195], s[68:69] offset:2048
	global_store_dwordx4 v187, v[196:199], s[68:69] offset:2064
	s_branch .Ldu_next
